# odd workgroups (odd XCDs) enter out-proj 30us late so their HBM-bound epilogues interleave with the even groups K-loops
# baseline (speedup 1.0000x reference)
; #define LAS __attribute__((address_space(3)))
;   DI bool next(int i, Unit& u) const {
;     const int L = i * G + c;
;     if (L >= 1040) return false;
;     int mt, nt;
;     if (L < 1024) { mt = 8 * (L >> 6) + (L & 7); nt = (L >> 3) & 7; }
;     else { const int j = L - 1024; mt = 128 + (j & 1); nt = j >> 1; }
;     u.pm = mt; u.pn = nt; u.kind = 2;
;     u.a = (const char*)p->Xb + (size_t)mt * TSTEP; u.b = (const char*)p->WoutT + (size_t)nt * TSTEP;
;     return true;
; __global__ void __launch_bounds__(NTHR) fwd_megakernel(Params p) {
;     ...
;     SchedOut S; S.p = &p; S.G = (int)gridDim.x; S.c = (int)blockIdx.x;
;     EpiAll E; E.p = &p; E.handoff = (gridDim.x == 256);
;     gemm_phase<EpiAll, SchedOut>((LAS unsigned char*)smem, S, E);
.LBB0_601:
	s_or_b64 exec, exec, s[0:1]
	v_mov_b32_e32 v8, v160
	s_barrier
	s_bitcmp1_b32 s70, 0
	s_cbranch_scc0 .Lstag_done
	s_memrealtime s[100:101]
	s_waitcnt lgkmcnt(0)
.Lstag_loop:
	s_sleep 8
	s_memrealtime s[0:1]
	s_waitcnt lgkmcnt(0)
	s_sub_u32 s0, s0, s100
	s_cmpk_lt_u32 s0, 3000
	s_cbranch_scc1 .Lstag_loop
.Lstag_done:
	s_cmpk_gt_i32 s70, 0x40f
	v_readfirstlane_b32 s2, v8
	s_cbranch_scc1 .LBB0_634
	s_cmpk_gt_i32 s70, 0x3ff
	s_cbranch_scc0 .LBB0_604
	s_add_i32 s0, s70, 0xfffffc00
	s_and_b32 s1, s70, 1
	s_or_b32 s24, s1, 0x80
	s_lshr_b32 s28, s0, 1
	s_cbranch_execz .LBB0_605
	s_branch .LBB0_606
